# v19 plus prep row loop (bf16 x + row sum of squares) software-pipelined: next row's four loads issued one row ahead
# speedup vs baseline: 1.0136x; 1.0136x over previous
.Lxp_entry:
	v_mov_b32_e32 v19, 0
	v_ashrrev_i32_e32 v1, 31, v0
	v_lshlrev_b64 v[14:15], 12, v[0:1]
	v_lshl_add_u64 v[14:15], v[2:3], 0, v[14:15]
	global_load_dwordx4 v[36:39], v[14:15], off
	global_load_dwordx4 v[40:43], v[14:15], off offset:16
	global_load_dwordx4 v[44:47], v[14:15], off offset:2048
	global_load_dwordx4 v[48:51], v[14:15], off offset:2064
.Lxp_loop:
	v_add_u32_e32 v18, s9, v0
	v_min_i32_e32 v18, s17, v18
	v_lshlrev_b64 v[20:21], 12, v[18:19]
	v_lshl_add_u64 v[20:21], v[2:3], 0, v[20:21]
	global_load_dwordx4 v[140:143], v[20:21], off
	global_load_dwordx4 v[144:147], v[20:21], off offset:16
	global_load_dwordx4 v[148:151], v[20:21], off offset:2048
	global_load_dwordx4 v[152:155], v[20:21], off offset:2064
	v_ashrrev_i32_e32 v1, 31, v0
	v_lshlrev_b64 v[26:27], 11, v[0:1]
	v_lshl_add_u64 v[34:35], v[4:5], 0, v[26:27]
	s_waitcnt vmcnt(7)
	v_cvt_pk_bf16_f32 v26, v36, v37
	v_cvt_pk_bf16_f32 v27, v38, v39
	s_waitcnt vmcnt(6)
	v_cvt_pk_bf16_f32 v28, v40, v41
	v_cvt_pk_bf16_f32 v29, v42, v43
	global_store_dwordx4 v[34:35], v[26:29], off
	v_pk_mul_f32 v[14:15], v[36:37], v[36:37]
	v_pk_mul_f32 v[22:23], v[38:39], v[38:39]
	v_add_f32_e32 v1, v14, v15
	v_add_f32_e32 v1, v1, v22
	v_pk_mul_f32 v[24:25], v[40:41], v[40:41]
	v_add_f32_e32 v1, v1, v23
	v_add_f32_e32 v1, v1, v24
	v_pk_mul_f32 v[30:31], v[42:43], v[42:43]
	v_add_f32_e32 v1, v1, v25
	v_add_f32_e32 v1, v1, v30
	v_add_f32_e32 v1, v1, v31
	s_waitcnt vmcnt(6)
	v_pk_mul_f32 v[14:15], v[44:45], v[44:45]
	v_add_f32_e32 v1, v1, v14
	v_pk_mul_f32 v[22:23], v[46:47], v[46:47]
	v_add_f32_e32 v1, v1, v15
	v_add_f32_e32 v1, v1, v22
	s_waitcnt vmcnt(5)
	v_pk_mul_f32 v[24:25], v[48:49], v[48:49]
	v_add_f32_e32 v1, v1, v23
	v_add_f32_e32 v1, v1, v24
	v_pk_mul_f32 v[30:31], v[50:51], v[50:51]
	v_add_f32_e32 v1, v1, v25
	v_add_f32_e32 v1, v1, v30
	v_add_f32_e32 v1, v1, v31
	s_waitcnt lgkmcnt(0)
	ds_bpermute_b32 v7, v8, v1
	v_cvt_pk_bf16_f32 v26, v44, v45
	v_cvt_pk_bf16_f32 v27, v46, v47
	v_cvt_pk_bf16_f32 v28, v48, v49
	v_cvt_pk_bf16_f32 v29, v50, v51
	s_waitcnt lgkmcnt(0)
	v_add_f32_e32 v1, v1, v7
	ds_bpermute_b32 v7, v9, v1
	global_store_dwordx4 v[34:35], v[26:29], off offset:1024
	s_waitcnt lgkmcnt(0)
	v_add_f32_e32 v1, v1, v7
	ds_bpermute_b32 v7, v10, v1
	s_waitcnt lgkmcnt(0)
	v_add_f32_e32 v1, v1, v7
	ds_bpermute_b32 v7, v11, v1
	s_waitcnt lgkmcnt(0)
	v_add_f32_e32 v1, v1, v7
	ds_bpermute_b32 v7, v12, v1
	s_waitcnt lgkmcnt(0)
	v_add_f32_e32 v1, v1, v7
	ds_bpermute_b32 v7, v13, v1
	s_and_saveexec_b64 s[2:3], vcc
	s_cbranch_execz .Lxp_ns0
	s_waitcnt lgkmcnt(0)
	v_add_f32_e32 v1, v1, v7
	v_ashrrev_i32_e32 v7, 31, v6
	v_cndmask_b32_e64 v1, 0, v1, s[0:1]
	v_lshl_add_u64 v[14:15], v[6:7], 2, s[12:13]
	global_store_dword v[14:15], v1, off
.Lxp_ns0:
	s_or_b64 exec, exec, s[2:3]
	v_add_u32_e32 v0, s9, v0
	v_cmp_lt_i32_e64 s[2:3], s17, v0
	s_or_b64 s[14:15], s[2:3], s[14:15]
	v_add_u32_e32 v6, s16, v6
	s_andn2_b64 exec, exec, s[14:15]
	s_cbranch_execz .Lxp_done
	v_add_u32_e32 v18, s9, v0
	v_min_i32_e32 v18, s17, v18
	v_lshlrev_b64 v[20:21], 12, v[18:19]
	v_lshl_add_u64 v[20:21], v[2:3], 0, v[20:21]
	global_load_dwordx4 v[36:39], v[20:21], off
	global_load_dwordx4 v[40:43], v[20:21], off offset:16
	global_load_dwordx4 v[44:47], v[20:21], off offset:2048
	global_load_dwordx4 v[48:51], v[20:21], off offset:2064
	v_ashrrev_i32_e32 v1, 31, v0
	v_lshlrev_b64 v[26:27], 11, v[0:1]
	v_lshl_add_u64 v[34:35], v[4:5], 0, v[26:27]
	s_waitcnt vmcnt(7)
	v_cvt_pk_bf16_f32 v26, v140, v141
	v_cvt_pk_bf16_f32 v27, v142, v143
	s_waitcnt vmcnt(6)
	v_cvt_pk_bf16_f32 v28, v144, v145
	v_cvt_pk_bf16_f32 v29, v146, v147
	global_store_dwordx4 v[34:35], v[26:29], off
	v_pk_mul_f32 v[14:15], v[140:141], v[140:141]
	v_pk_mul_f32 v[22:23], v[142:143], v[142:143]
	v_add_f32_e32 v1, v14, v15
	v_add_f32_e32 v1, v1, v22
	v_pk_mul_f32 v[24:25], v[144:145], v[144:145]
	v_add_f32_e32 v1, v1, v23
	v_add_f32_e32 v1, v1, v24
	v_pk_mul_f32 v[30:31], v[146:147], v[146:147]
	v_add_f32_e32 v1, v1, v25
	v_add_f32_e32 v1, v1, v30
	v_add_f32_e32 v1, v1, v31
	s_waitcnt vmcnt(6)
	v_pk_mul_f32 v[14:15], v[148:149], v[148:149]
	v_add_f32_e32 v1, v1, v14
	v_pk_mul_f32 v[22:23], v[150:151], v[150:151]
	v_add_f32_e32 v1, v1, v15
	v_add_f32_e32 v1, v1, v22
	s_waitcnt vmcnt(5)
	v_pk_mul_f32 v[24:25], v[152:153], v[152:153]
	v_add_f32_e32 v1, v1, v23
	v_add_f32_e32 v1, v1, v24
	v_pk_mul_f32 v[30:31], v[154:155], v[154:155]
	v_add_f32_e32 v1, v1, v25
	v_add_f32_e32 v1, v1, v30
	v_add_f32_e32 v1, v1, v31
	s_waitcnt lgkmcnt(0)
	ds_bpermute_b32 v7, v8, v1
	v_cvt_pk_bf16_f32 v26, v148, v149
	v_cvt_pk_bf16_f32 v27, v150, v151
	v_cvt_pk_bf16_f32 v28, v152, v153
	v_cvt_pk_bf16_f32 v29, v154, v155
	s_waitcnt lgkmcnt(0)
	v_add_f32_e32 v1, v1, v7
	ds_bpermute_b32 v7, v9, v1
	global_store_dwordx4 v[34:35], v[26:29], off offset:1024
	s_waitcnt lgkmcnt(0)
	v_add_f32_e32 v1, v1, v7
	ds_bpermute_b32 v7, v10, v1
	s_waitcnt lgkmcnt(0)
	v_add_f32_e32 v1, v1, v7
	ds_bpermute_b32 v7, v11, v1
	s_waitcnt lgkmcnt(0)
	v_add_f32_e32 v1, v1, v7
	ds_bpermute_b32 v7, v12, v1
	s_waitcnt lgkmcnt(0)
	v_add_f32_e32 v1, v1, v7
	ds_bpermute_b32 v7, v13, v1
	s_and_saveexec_b64 s[2:3], vcc
	s_cbranch_execz .Lxp_ns1
	s_waitcnt lgkmcnt(0)
	v_add_f32_e32 v1, v1, v7
	v_ashrrev_i32_e32 v7, 31, v6
	v_cndmask_b32_e64 v1, 0, v1, s[0:1]
	v_lshl_add_u64 v[14:15], v[6:7], 2, s[12:13]
	global_store_dword v[14:15], v1, off
.Lxp_ns1:
	s_or_b64 exec, exec, s[2:3]
	v_add_u32_e32 v0, s9, v0
	v_cmp_lt_i32_e64 s[2:3], s17, v0
	s_or_b64 s[14:15], s[2:3], s[14:15]
	v_add_u32_e32 v6, s16, v6
	s_andn2_b64 exec, exec, s[14:15]
	s_cbranch_execz .Lxp_done
	s_branch .Lxp_loop
.Lxp_done:
	s_waitcnt vmcnt(0)
.LBB0_71:
	s_or_b64 exec, exec, s[10:11]
	v_lshl_add_u32 v0, s88, 9, v16
	s_mov_b32 s0, 0x10000
	v_cmp_gt_i32_e32 vcc, s0, v0
	s_and_saveexec_b64 s[0:1], vcc
	s_cbranch_execz .LBB0_74
	v_and_b32_e32 v1, 31, v16
	v_cvt_f32_ubyte0_e32 v1, v1
	v_mul_f32_e32 v2, 0xbed49a78, v1
	s_mov_b32 s9, 0xc2fc0000
	v_mov_b32_e32 v3, 0x42800000
	v_cmp_gt_f32_e32 vcc, s9, v2
	s_add_u32 s2, s6, 0x1ada0000
	s_addc_u32 s3, s7, 0
	v_cndmask_b32_e32 v2, 0, v3, vcc
	v_fmac_f32_e32 v2, 0xbed49a78, v1
	v_exp_f32_e32 v1, v2
	v_not_b32_e32 v2, 63
	s_add_u32 s6, s6, 0x1ade0000
	v_cndmask_b32_e32 v2, 0, v2, vcc
	s_mov_b32 s10, 0x6dc9c883
	s_addc_u32 s7, s7, 0
	s_lshl_b32 s12, s8, 9
	v_ldexp_f32 v2, v1, v2
	s_mov_b64 s[8:9], 0
	s_mov_b32 s11, 0x3fc45f30
	s_mov_b32 s13, 0xffff
